# NSA item entry: L2 warm-up touch of the token's branch-gate record issued with the first loads
# baseline (speedup 1.0000x reference)
; #define MAKE_RSRC(PTR) __builtin_amdgcn_make_buffer_rsrc((void*)(PTR), 0, 0x7fffffff, 0x00020000)
; #define ISSUE_TILE(RK, RV, T, LDV)                                                   \
;   {                                                                                  \
;     pk0 = BLOAD(RK, koff, (T)*8192);                                                 \
;     pv0 = BLOAD(RV, ((LDV) == 512) ? voffc : voffs, (T)*128);                        \
;   }
; DI void nsa_item(int wv0, PP p, int item, unsigned char* smem) {
;   const int tid = my_tid(wv0), lane = tid & 63, wv = wv0 & 3, hp = wv0 >> 2, l15 = lane & 15, lg = lane >> 4;
;   const int i = 127 - (item >> 3), bg = item & 7, b = bg >> 1, g = bg & 1;
;   u16* sK = (u16*)smem;
;   u16* sV = sK + 64 * 72;
;   float* sImp0 = (float*)(smem + 55296);
;   float* sImp = sImp0 + hp * (64 * 132);
;   u64* sUni = (u64*)(smem + 55296 + 2 * 64 * 132 * 4);
;   u64* sSel = sUni + 16;
;   const int t0 = i * 64, qloc = 16 * wv + l15, tq = t0 + qloc;
;   const unsigned tokq = (unsigned)(b * S_ + tq);
;   const float* NGb = (const float*)(p->ws + OFF_NG);
;   const unsigned ngoff = tokq * 24 + g * 12 + hp * 6;
;   float* ACCb = p->out;
;   const unsigned aoff = tokq * 512 + g * 256 + hp * 128 + 4 * lg;
;   const unsigned qoff = tokq * 512 + g * 256 + hp * 128 + lg * 8;
;   const int lrow = tid >> 3, lpart = tid & 7;
;   const unsigned koff = (lrow * 64 + lpart * 8) * 2, voffc = (lrow * 512 + lpart * 8) * 2, voffs = (lrow * S_ + lpart * 8) * 2;
;   for (int e = tid; e < 2 * 64 * 132; e += NT_) sImp0[e] = 0.f;
;   bf16x8 qf[2][2];
;   f32x4 O[2][4];
;   float m[2], l[2], ps[4][4];
;   u32x4 pk0, pv0;
;   auto nomask = [](int, int) { return true; };
;     ...
;   {
;     const u16* Kc0 = (const u16*)(p->ws + OFF_KCC) + (size_t)bg * 512 * 64;
;     const u16* Vc0 = (const u16*)(p->ws + OFF_VCT) + (size_t)bg * 64 * 512;
;     const int nE = (4 * i + 3) < 511 ? (4 * i + 3) : 511;
;     const int nkb = (nE + 63) >> 6;
;     const __amdgpu_buffer_rsrc_t rK = MAKE_RSRC(Kc0), rV = MAKE_RSRC(Vc0);
;     LOAD_Q(OFF_QRAW)
;     RESET_STATE()
;     ISSUE_TILE(rK, rV, 0, 512)
.LBB0_796:
	s_or_b64 exec, exec, s[2:3]
	v_and_b32_e32 v155, 15, v26
	s_ashr_i32 s88, s16, 3
	s_sub_i32 s33, 0x7f, s88
	v_or_b32_e32 v160, s45, v155
	s_lshl_b32 s2, s16, 12
	s_and_b32 s40, s16, 1
	v_lshl_or_b32 v151, s33, 6, v160
	s_and_b32 s2, s2, 0x6000
	v_add_u32_e32 v74, s2, v151
	s_lshl_b32 s2, s40, 8
	v_readlane_b32 s3, v246, 5
	s_and_b32 s84, s16, 7
	s_add_i32 s2, s2, s3
	v_lshl_add_u32 v72, v74, 9, s2
	s_lshl_b32 s2, s84, 16
	v_readlane_b32 s3, v247, 51
	s_add_u32 s68, s3, s2
	v_readlane_b32 s3, v247, 52
	s_addc_u32 s3, s3, 0
	s_lshl_b32 s4, s33, 2
	s_or_b32 s5, s4, 3
	s_addk_i32 s4, 0x42
	v_bfe_u32 v73, v26, 4, 2
	s_lshr_b32 s4, s4, 6
	s_and_b32 s69, s3, 0xffff
	v_lshlrev_b32_e32 v156, 3, v73
	v_lshlrev_b32_e32 v2, 3, v26
	s_cmpk_lt_u32 s5, 0x1ff
	v_readlane_b32 s3, v247, 53
	v_or_b32_e32 v0, v72, v156
	v_and_b32_e32 v2, 56, v2
	v_readlane_b32 s6, v247, 55
	s_cselect_b32 s41, s4, 8
	s_add_u32 s36, s3, s2
	v_readlane_b32 s2, v247, 54
	v_ashrrev_i32_e32 v70, 3, v26
	v_lshlrev_b32_e32 v68, 1, v2
	v_readlane_b32 s7, v247, 56
	v_or_b32_e32 v66, 32, v0
	v_mov_b32_e32 v67, v1
	v_or_b32_e32 v64, 64, v0
	v_mov_b32_e32 v65, v1
	v_or_b32_e32 v62, 0x60, v0
	v_mov_b32_e32 v63, v1
	s_addc_u32 s2, s2, 0
	v_lshl_or_b32 v75, v70, 10, v68
	v_lshl_add_u64 v[2:3], v[0:1], 1, s[6:7]
	v_lshl_add_u64 v[6:7], v[66:67], 1, s[6:7]
	v_lshl_add_u64 v[10:11], v[64:65], 1, s[6:7]
	v_lshl_add_u64 v[14:15], v[62:63], 1, s[6:7]
	s_and_b32 s37, s2, 0xffff
	s_mov_b32 s38, s70
	s_mov_b32 s39, s71
	v_lshl_or_b32 v152, v70, 7, v68
	global_load_dwordx4 v[2:5], v[2:3], off
	s_nop 0
	global_load_dwordx4 v[6:9], v[6:7], off
	s_nop 0
	global_load_dwordx4 v[10:13], v[10:11], off
	s_nop 0
	global_load_dwordx4 v[14:17], v[14:15], off
	s_nop 0
	buffer_load_dwordx4 v[22:25], v75, s[36:39], 0 offen
	buffer_load_dwordx4 v[18:21], v152, s[68:71], 0 offen
	v_mul_u32_u24_e32 v200, 0x60, v74
	global_load_dword v201, v200, s[94:95]
	global_load_dword v202, v200, s[94:95] offset:92
	s_movk_i32 s2, 0x48
	v_and_b32_e32 v71, 63, v26
	v_mul_lo_u32 v27, v70, s2
	v_lshlrev_b32_e32 v69, 1, v27
	v_and_b32_e32 v27, 48, v26
	v_or_b32_e32 v157, 48, v71
	v_lshl_add_u32 v77, v73, 6, v147
	s_mov_b32 s42, 0
	v_add3_u32 v76, 32, v68, v69
	v_add_u32_e32 v158, 32, v27
	v_mul_u32_u24_e32 v27, 0x90, v155
	v_mul_u32_u24_e32 v28, 0x90, v157
	v_mov_b32_e32 v30, 0
	v_mov_b32_e32 v31, 0xf149f2ca
	s_movk_i32 s43, 0x80
	s_movk_i32 s44, 0x2000
	v_mov_b32_e32 v29, v77
	v_mov_b32_e32 v34, 0xf149f2ca
	v_mov_b32_e32 v32, 0
